# swiglu K-loop LDS-DMA addressing via SGPR base + 32-bit voffset (16 fewer 64-bit VALU per iteration) on top of peel/flat2global
# speedup vs baseline: 1.0205x; 1.0051x over previous
.LBB0_527:
	s_ashr_i32 s19, s18, 31
	s_lshl_b64 s[20:21], s[18:19], 19
	s_add_u32 s20, s50, s20
	s_addc_u32 s21, s51, s21
	s_and_b64 s[22:23], s[4:5], exec
	s_cselect_b32 s19, s21, s29
	s_cselect_b32 s25, s20, s28
	s_ashr_i32 s17, s16, 31
	s_lshl_b64 s[22:23], s[16:17], 19
	s_add_u32 s22, s46, s22
	s_addc_u32 s23, s47, s23
	s_and_b64 s[30:31], s[4:5], exec
	s_cselect_b32 s0, s23, s27
	s_cselect_b32 s17, s22, s26
	s_mov_b64 s[30:31], 0
	s_mov_b32 s43, -2
	s_add_u32 s34, s30, 0x100
	s_addc_u32 s35, s31, 0
	s_add_u32 s38, s30, 0xfffff900
	v_cmp_gt_u64_e32 vcc, s[34:35], v[192:193]
	s_addc_u32 s39, s31, -1
	s_and_b64 s[36:37], vcc, exec
	s_cselect_b32 s34, s38, s34
	s_cselect_b32 s35, s39, s35
	s_add_u32 s36, s28, s34
	s_addc_u32 s37, s29, s35
	s_add_u32 s76, s26, s34
	s_addc_u32 s77, s27, s35
	s_add_i32 s86, 0, 0x10000
	s_cmp_eq_u32 s43, 12
	s_cselect_b32 s39, s19, s37
	s_cselect_b32 s38, s25, s36
	v_add_u32_e32 v138, s86, v141
	s_cselect_b32 s37, s0, s77
	s_cselect_b32 s36, s17, s76
	s_add_i32 s76, 0, 0x14000
	ds_read_b128 v[96:99], v138
	ds_read_b128 v[150:153], v138 offset:1024
	ds_read_b128 v[154:157], v138 offset:2048
	ds_read_b128 v[158:161], v138 offset:3072
	v_add_u32_e32 v138, s76, v141
	ds_read_b128 v[162:165], v138
	ds_read_b128 v[166:169], v138 offset:1024
	ds_read_b128 v[170:173], v138 offset:2048
	ds_read_b128 v[174:177], v138 offset:3072
	s_add_u32 s30, s28, s30
	s_addc_u32 s31, s29, s31
	s_add_u32 s30, s30, 0x40080
	s_addc_u32 s31, s31, 0
	s_add_i32 m0, s60, 0xc000
	ds_read_b128 v[178:181], v149
	ds_read_b128 v[182:185], v149 offset:1024
	ds_read_b128 v[202:205], v149 offset:2048
	ds_read_b128 v[206:209], v149 offset:3072
	ds_read_b128 v[210:213], v149 offset:4096
	ds_read_b128 v[214:217], v149 offset:5120
	ds_read_b128 v[218:221], v149 offset:6144
	ds_read_b128 v[222:225], v149 offset:7168
	global_load_lds_dwordx4 v136, s[30:31]
	s_add_i32 m0, s60, 0xe000
	s_nop 0
	global_load_lds_dwordx4 v134, s[30:31]
	s_waitcnt vmcnt(8)
	s_waitcnt lgkmcnt(0)
	s_barrier
	s_setprio 1
	s_waitcnt lgkmcnt(0)
	v_mfma_f32_16x16x32_bf16 v[128:131], v[96:99], v[178:181], 0
	v_mfma_f32_16x16x32_bf16 v[120:123], v[154:157], v[178:181], 0
	v_mfma_f32_16x16x32_bf16 v[112:115], v[96:99], v[202:205], 0
	v_mfma_f32_16x16x32_bf16 v[104:107], v[154:157], v[202:205], 0
	v_mfma_f32_16x16x32_bf16 v[92:95], v[96:99], v[210:213], 0
	v_mfma_f32_16x16x32_bf16 v[84:87], v[154:157], v[210:213], 0
	v_mfma_f32_16x16x32_bf16 v[76:79], v[96:99], v[218:221], 0
	v_mfma_f32_16x16x32_bf16 v[68:71], v[154:157], v[218:221], 0
	v_mfma_f32_16x16x32_bf16 v[128:131], v[150:153], v[182:185], v[128:131]
	v_mfma_f32_16x16x32_bf16 v[120:123], v[158:161], v[182:185], v[120:123]
	v_mfma_f32_16x16x32_bf16 v[112:115], v[150:153], v[206:209], v[112:115]
	v_mfma_f32_16x16x32_bf16 v[104:107], v[158:161], v[206:209], v[104:107]
	v_mfma_f32_16x16x32_bf16 v[92:95], v[150:153], v[214:217], v[92:95]
	v_mfma_f32_16x16x32_bf16 v[84:87], v[158:161], v[214:217], v[84:87]
	v_mfma_f32_16x16x32_bf16 v[76:79], v[150:153], v[222:225], v[76:79]
	v_mfma_f32_16x16x32_bf16 v[68:71], v[158:161], v[222:225], v[68:71]
	s_setprio 0
	s_setprio 1
	v_mfma_f32_16x16x32_bf16 v[124:127], v[162:165], v[178:181], 0
	v_mfma_f32_16x16x32_bf16 v[116:119], v[170:173], v[178:181], 0
	v_mfma_f32_16x16x32_bf16 v[108:111], v[162:165], v[202:205], 0
	v_mfma_f32_16x16x32_bf16 v[100:103], v[170:173], v[202:205], 0
	v_mfma_f32_16x16x32_bf16 v[88:91], v[162:165], v[210:213], 0
	v_mfma_f32_16x16x32_bf16 v[80:83], v[170:173], v[210:213], 0
	v_mfma_f32_16x16x32_bf16 v[72:75], v[162:165], v[218:221], 0
	v_mfma_f32_16x16x32_bf16 v[64:67], v[170:173], v[218:221], 0
	v_mfma_f32_16x16x32_bf16 v[124:127], v[166:169], v[182:185], v[124:127]
	v_mfma_f32_16x16x32_bf16 v[116:119], v[174:177], v[182:185], v[116:119]
	v_mfma_f32_16x16x32_bf16 v[108:111], v[166:169], v[206:209], v[108:111]
	v_mfma_f32_16x16x32_bf16 v[100:103], v[174:177], v[206:209], v[100:103]
	v_mfma_f32_16x16x32_bf16 v[88:91], v[166:169], v[214:217], v[88:91]
	v_mfma_f32_16x16x32_bf16 v[80:83], v[174:177], v[214:217], v[80:83]
	v_mfma_f32_16x16x32_bf16 v[72:75], v[166:169], v[222:225], v[72:75]
	v_mfma_f32_16x16x32_bf16 v[64:67], v[174:177], v[222:225], v[64:67]
	s_setprio 0
	s_barrier
	s_add_i32 s30, s86, s56
	s_mov_b32 m0, s30
	ds_read_b128 v[178:181], v149 offset:16384
	ds_read_b128 v[182:185], v149 offset:17408
	ds_read_b128 v[202:205], v149 offset:18432
	ds_read_b128 v[206:209], v149 offset:19456
	ds_read_b128 v[210:213], v149 offset:20480
	ds_read_b128 v[214:217], v149 offset:21504
	ds_read_b128 v[218:221], v149 offset:22528
	ds_read_b128 v[222:225], v149 offset:23552
	global_load_lds_dwordx4 v188, s[36:37]
	s_add_i32 m0, s30, 0x2000
	s_add_u32 s30, s36, 0x40000
	s_addc_u32 s31, s37, 0
	s_add_i32 s76, s76, s56
	global_load_lds_dwordx4 v132, s[36:37]
	s_mov_b32 m0, s76
	s_nop 0
	global_load_lds_dwordx4 v188, s[30:31]
	s_add_i32 m0, s76, 0x2000
	s_nop 0
	global_load_lds_dwordx4 v132, s[30:31]
	s_mov_b32 m0, s60
	s_nop 0
	global_load_lds_dwordx4 v136, s[38:39]
	s_mov_b32 m0, s71
	s_nop 0
	global_load_lds_dwordx4 v134, s[38:39]
	s_waitcnt vmcnt(8)
	s_waitcnt lgkmcnt(0)
	s_barrier
	s_setprio 1
	s_waitcnt lgkmcnt(0)
	v_mfma_f32_16x16x32_bf16 v[60:63], v[96:99], v[178:181], 0
	v_mfma_f32_16x16x32_bf16 v[52:55], v[154:157], v[178:181], 0
	v_mfma_f32_16x16x32_bf16 v[44:47], v[96:99], v[202:205], 0
	v_mfma_f32_16x16x32_bf16 v[36:39], v[154:157], v[202:205], 0
	v_mfma_f32_16x16x32_bf16 v[28:31], v[96:99], v[210:213], 0
	v_mfma_f32_16x16x32_bf16 v[20:23], v[154:157], v[210:213], 0
	v_mfma_f32_16x16x32_bf16 v[12:15], v[96:99], v[218:221], 0
	v_mfma_f32_16x16x32_bf16 v[4:7], v[154:157], v[218:221], 0
	v_mfma_f32_16x16x32_bf16 v[60:63], v[150:153], v[182:185], v[60:63]
	v_mfma_f32_16x16x32_bf16 v[52:55], v[158:161], v[182:185], v[52:55]
	v_mfma_f32_16x16x32_bf16 v[44:47], v[150:153], v[206:209], v[44:47]
	v_mfma_f32_16x16x32_bf16 v[36:39], v[158:161], v[206:209], v[36:39]
	v_mfma_f32_16x16x32_bf16 v[28:31], v[150:153], v[214:217], v[28:31]
	v_mfma_f32_16x16x32_bf16 v[20:23], v[158:161], v[214:217], v[20:23]
	v_mfma_f32_16x16x32_bf16 v[12:15], v[150:153], v[222:225], v[12:15]
	v_mfma_f32_16x16x32_bf16 v[4:7], v[158:161], v[222:225], v[4:7]
	s_setprio 0
	s_setprio 1
	v_mfma_f32_16x16x32_bf16 v[56:59], v[162:165], v[178:181], 0
	v_mfma_f32_16x16x32_bf16 v[48:51], v[170:173], v[178:181], 0
	v_mfma_f32_16x16x32_bf16 v[40:43], v[162:165], v[202:205], 0
	v_mfma_f32_16x16x32_bf16 v[32:35], v[170:173], v[202:205], 0
	v_mfma_f32_16x16x32_bf16 v[24:27], v[162:165], v[210:213], 0
	v_mfma_f32_16x16x32_bf16 v[16:19], v[170:173], v[210:213], 0
	v_mfma_f32_16x16x32_bf16 v[8:11], v[162:165], v[218:221], 0
	v_mfma_f32_16x16x32_bf16 v[0:3], v[170:173], v[218:221], 0
	v_mfma_f32_16x16x32_bf16 v[56:59], v[166:169], v[182:185], v[56:59]
	v_mfma_f32_16x16x32_bf16 v[48:51], v[174:177], v[182:185], v[48:51]
	v_mfma_f32_16x16x32_bf16 v[40:43], v[166:169], v[206:209], v[40:43]
	v_mfma_f32_16x16x32_bf16 v[32:35], v[174:177], v[206:209], v[32:35]
	v_mfma_f32_16x16x32_bf16 v[24:27], v[166:169], v[214:217], v[24:27]
	v_mfma_f32_16x16x32_bf16 v[16:19], v[174:177], v[214:217], v[16:19]
	v_mfma_f32_16x16x32_bf16 v[8:11], v[166:169], v[222:225], v[8:11]
	v_mfma_f32_16x16x32_bf16 v[0:3], v[174:177], v[222:225], v[0:3]
	s_setprio 0
	s_barrier
	s_add_i32 s76, 0, 0x18000
	v_add_u32_e32 v138, s76, v141
	s_add_i32 s77, 0, 0x1c000
	ds_read_b128 v[96:99], v138
	ds_read_b128 v[150:153], v138 offset:1024
	ds_read_b128 v[154:157], v138 offset:2048
	ds_read_b128 v[158:161], v138 offset:3072
	v_add_u32_e32 v138, s77, v141
	ds_read_b128 v[162:165], v138
	ds_read_b128 v[166:169], v138 offset:1024
	ds_read_b128 v[170:173], v138 offset:2048
	ds_read_b128 v[174:177], v138 offset:3072
	s_add_u32 s30, s38, 0x40000
	s_addc_u32 s31, s39, 0
	s_mov_b32 m0, s87
	ds_read_b128 v[178:181], v149 offset:32768
	ds_read_b128 v[182:185], v149 offset:33792
	ds_read_b128 v[202:205], v149 offset:34816
	ds_read_b128 v[206:209], v149 offset:35840
	ds_read_b128 v[210:213], v149 offset:36864
	ds_read_b128 v[214:217], v149 offset:37888
	ds_read_b128 v[218:221], v149 offset:38912
	ds_read_b128 v[222:225], v149 offset:39936
	global_load_lds_dwordx4 v136, s[30:31]
	s_mov_b32 m0, s89
	s_nop 0
	global_load_lds_dwordx4 v134, s[30:31]
	s_waitcnt vmcnt(8)
	s_waitcnt lgkmcnt(0)
	s_barrier
	s_setprio 1
	s_waitcnt lgkmcnt(0)
	v_mfma_f32_16x16x32_bf16 v[128:131], v[96:99], v[178:181], v[128:131]
	v_mfma_f32_16x16x32_bf16 v[120:123], v[154:157], v[178:181], v[120:123]
	v_mfma_f32_16x16x32_bf16 v[112:115], v[96:99], v[202:205], v[112:115]
	v_mfma_f32_16x16x32_bf16 v[104:107], v[154:157], v[202:205], v[104:107]
	v_mfma_f32_16x16x32_bf16 v[92:95], v[96:99], v[210:213], v[92:95]
	v_mfma_f32_16x16x32_bf16 v[84:87], v[154:157], v[210:213], v[84:87]
	v_mfma_f32_16x16x32_bf16 v[76:79], v[96:99], v[218:221], v[76:79]
	v_mfma_f32_16x16x32_bf16 v[68:71], v[154:157], v[218:221], v[68:71]
	v_mfma_f32_16x16x32_bf16 v[128:131], v[150:153], v[182:185], v[128:131]
	v_mfma_f32_16x16x32_bf16 v[120:123], v[158:161], v[182:185], v[120:123]
	v_mfma_f32_16x16x32_bf16 v[112:115], v[150:153], v[206:209], v[112:115]
	v_mfma_f32_16x16x32_bf16 v[104:107], v[158:161], v[206:209], v[104:107]
	v_mfma_f32_16x16x32_bf16 v[92:95], v[150:153], v[214:217], v[92:95]
	v_mfma_f32_16x16x32_bf16 v[84:87], v[158:161], v[214:217], v[84:87]
	v_mfma_f32_16x16x32_bf16 v[76:79], v[150:153], v[222:225], v[76:79]
	v_mfma_f32_16x16x32_bf16 v[68:71], v[158:161], v[222:225], v[68:71]
	s_setprio 0
	s_setprio 1
	v_mfma_f32_16x16x32_bf16 v[124:127], v[162:165], v[178:181], v[124:127]
	v_mfma_f32_16x16x32_bf16 v[116:119], v[170:173], v[178:181], v[116:119]
	v_mfma_f32_16x16x32_bf16 v[108:111], v[162:165], v[202:205], v[108:111]
	v_mfma_f32_16x16x32_bf16 v[100:103], v[170:173], v[202:205], v[100:103]
	v_mfma_f32_16x16x32_bf16 v[88:91], v[162:165], v[210:213], v[88:91]
	v_mfma_f32_16x16x32_bf16 v[80:83], v[170:173], v[210:213], v[80:83]
	v_mfma_f32_16x16x32_bf16 v[72:75], v[162:165], v[218:221], v[72:75]
	v_mfma_f32_16x16x32_bf16 v[64:67], v[170:173], v[218:221], v[64:67]
	v_mfma_f32_16x16x32_bf16 v[124:127], v[166:169], v[182:185], v[124:127]
	v_mfma_f32_16x16x32_bf16 v[116:119], v[174:177], v[182:185], v[116:119]
	v_mfma_f32_16x16x32_bf16 v[108:111], v[166:169], v[206:209], v[108:111]
	v_mfma_f32_16x16x32_bf16 v[100:103], v[174:177], v[206:209], v[100:103]
	v_mfma_f32_16x16x32_bf16 v[88:91], v[166:169], v[214:217], v[88:91]
	v_mfma_f32_16x16x32_bf16 v[80:83], v[174:177], v[214:217], v[80:83]
	v_mfma_f32_16x16x32_bf16 v[72:75], v[166:169], v[222:225], v[72:75]
	v_mfma_f32_16x16x32_bf16 v[64:67], v[174:177], v[222:225], v[64:67]
	s_setprio 0
	s_barrier
	s_add_i32 s30, s76, s56
	s_add_u32 s100, s36, 0x80
	s_addc_u32 s101, s37, 0
	s_mov_b32 m0, s30
	ds_read_b128 v[178:181], v149 offset:49152
	ds_read_b128 v[182:185], v149 offset:50176
	ds_read_b128 v[202:205], v149 offset:51200
	ds_read_b128 v[206:209], v149 offset:52224
	ds_read_b128 v[210:213], v149 offset:53248
	ds_read_b128 v[214:217], v149 offset:54272
	ds_read_b128 v[218:221], v149 offset:55296
	ds_read_b128 v[222:225], v149 offset:56320
	global_load_lds_dwordx4 v188, s[100:101]
	s_add_i32 m0, s30, 0x2000
	s_add_u32 s30, s36, 0x40080
	s_addc_u32 s31, s37, 0
	s_add_i32 s36, s77, s56
	global_load_lds_dwordx4 v132, s[100:101]
	s_mov_b32 m0, s36
	s_nop 0
	global_load_lds_dwordx4 v188, s[30:31]
	s_add_i32 m0, s36, 0x2000
	s_nop 0
	global_load_lds_dwordx4 v132, s[30:31]
	s_add_u32 s100, s38, 0x80
	s_addc_u32 s101, s39, 0
	s_mov_b32 m0, s90
	s_nop 0
	global_load_lds_dwordx4 v136, s[100:101]
	s_mov_b32 m0, s91
	s_nop 0
	global_load_lds_dwordx4 v134, s[100:101]
	s_waitcnt vmcnt(8)
	s_waitcnt lgkmcnt(0)
	s_barrier
	s_setprio 1
	s_waitcnt lgkmcnt(0)
	v_mfma_f32_16x16x32_bf16 v[60:63], v[96:99], v[178:181], v[60:63]
	v_mfma_f32_16x16x32_bf16 v[52:55], v[154:157], v[178:181], v[52:55]
	v_mfma_f32_16x16x32_bf16 v[44:47], v[96:99], v[202:205], v[44:47]
	v_mfma_f32_16x16x32_bf16 v[36:39], v[154:157], v[202:205], v[36:39]
	v_mfma_f32_16x16x32_bf16 v[28:31], v[96:99], v[210:213], v[28:31]
	v_mfma_f32_16x16x32_bf16 v[20:23], v[154:157], v[210:213], v[20:23]
	v_mfma_f32_16x16x32_bf16 v[12:15], v[96:99], v[218:221], v[12:15]
	v_mfma_f32_16x16x32_bf16 v[4:7], v[154:157], v[218:221], v[4:7]
	v_mfma_f32_16x16x32_bf16 v[60:63], v[150:153], v[182:185], v[60:63]
	v_mfma_f32_16x16x32_bf16 v[52:55], v[158:161], v[182:185], v[52:55]
	v_mfma_f32_16x16x32_bf16 v[44:47], v[150:153], v[206:209], v[44:47]
	v_mfma_f32_16x16x32_bf16 v[36:39], v[158:161], v[206:209], v[36:39]
	v_mfma_f32_16x16x32_bf16 v[28:31], v[150:153], v[214:217], v[28:31]
	v_mfma_f32_16x16x32_bf16 v[20:23], v[158:161], v[214:217], v[20:23]
	v_mfma_f32_16x16x32_bf16 v[12:15], v[150:153], v[222:225], v[12:15]
	v_mfma_f32_16x16x32_bf16 v[4:7], v[158:161], v[222:225], v[4:7]
	s_setprio 0
	s_setprio 1
	v_mfma_f32_16x16x32_bf16 v[56:59], v[162:165], v[178:181], v[56:59]
	v_mfma_f32_16x16x32_bf16 v[48:51], v[170:173], v[178:181], v[48:51]
	v_mfma_f32_16x16x32_bf16 v[40:43], v[162:165], v[202:205], v[40:43]
	v_mfma_f32_16x16x32_bf16 v[32:35], v[170:173], v[202:205], v[32:35]
	v_mfma_f32_16x16x32_bf16 v[24:27], v[162:165], v[210:213], v[24:27]
	v_mfma_f32_16x16x32_bf16 v[16:19], v[170:173], v[210:213], v[16:19]
	v_mfma_f32_16x16x32_bf16 v[8:11], v[162:165], v[218:221], v[8:11]
	v_mfma_f32_16x16x32_bf16 v[0:3], v[170:173], v[218:221], v[0:3]
	v_mfma_f32_16x16x32_bf16 v[56:59], v[166:169], v[182:185], v[56:59]
	v_mfma_f32_16x16x32_bf16 v[48:51], v[174:177], v[182:185], v[48:51]
	v_mfma_f32_16x16x32_bf16 v[40:43], v[166:169], v[206:209], v[40:43]
	v_mfma_f32_16x16x32_bf16 v[32:35], v[174:177], v[206:209], v[32:35]
	v_mfma_f32_16x16x32_bf16 v[24:27], v[166:169], v[214:217], v[24:27]
	v_mfma_f32_16x16x32_bf16 v[16:19], v[174:177], v[214:217], v[16:19]
	v_mfma_f32_16x16x32_bf16 v[8:11], v[166:169], v[222:225], v[8:11]
	v_mfma_f32_16x16x32_bf16 v[0:3], v[174:177], v[222:225], v[0:3]
	s_setprio 0
	s_barrier
	s_add_i32 s43, s43, 2
	s_cmp_gt_u32 s43, 13
	s_mov_b64 s[30:31], s[34:35]
	s_cbranch_scc1 .Lpeel_exit_swiglu
.LBB0_528:
	s_add_u32 s34, s30, 0x100
	s_addc_u32 s35, s31, 0
	s_add_u32 s38, s30, 0xfffff900
	v_cmp_gt_u64_e32 vcc, s[34:35], v[192:193]
	s_addc_u32 s39, s31, -1
	s_and_b64 s[36:37], vcc, exec
	s_cselect_b32 s34, s38, s34
	s_cselect_b32 s35, s39, s35
	s_add_u32 s36, s28, s34
	s_addc_u32 s37, s29, s35
	s_add_u32 s76, s26, s34
	s_addc_u32 s77, s27, s35
	s_add_i32 s86, 0, 0x10000
	s_cmp_eq_u32 s43, 12
	s_cselect_b32 s39, s19, s37
	s_cselect_b32 s38, s25, s36
	v_add_u32_e32 v138, s86, v141
	s_cselect_b32 s37, s0, s77
	s_cselect_b32 s36, s17, s76
	s_add_i32 s76, 0, 0x14000
	ds_read_b128 v[96:99], v138
	ds_read_b128 v[150:153], v138 offset:1024
	ds_read_b128 v[154:157], v138 offset:2048
	ds_read_b128 v[158:161], v138 offset:3072
	v_add_u32_e32 v138, s76, v141
	ds_read_b128 v[162:165], v138
	ds_read_b128 v[166:169], v138 offset:1024
	ds_read_b128 v[170:173], v138 offset:2048
	ds_read_b128 v[174:177], v138 offset:3072
	s_add_u32 s30, s28, s30
	s_addc_u32 s31, s29, s31
	s_add_u32 s30, s30, 0x40080
	s_addc_u32 s31, s31, 0
	s_add_i32 m0, s60, 0xc000
	ds_read_b128 v[178:181], v149
	ds_read_b128 v[182:185], v149 offset:1024
	ds_read_b128 v[202:205], v149 offset:2048
	ds_read_b128 v[206:209], v149 offset:3072
	ds_read_b128 v[210:213], v149 offset:4096
	ds_read_b128 v[214:217], v149 offset:5120
	ds_read_b128 v[218:221], v149 offset:6144
	ds_read_b128 v[222:225], v149 offset:7168
	global_load_lds_dwordx4 v136, s[30:31]
	s_add_i32 m0, s60, 0xe000
	s_nop 0
	global_load_lds_dwordx4 v134, s[30:31]
	s_waitcnt vmcnt(8)
	s_waitcnt lgkmcnt(0)
	s_barrier
	s_setprio 1
	s_waitcnt lgkmcnt(0)
	v_mfma_f32_16x16x32_bf16 v[128:131], v[96:99], v[178:181], v[128:131]
	v_mfma_f32_16x16x32_bf16 v[120:123], v[154:157], v[178:181], v[120:123]
	v_mfma_f32_16x16x32_bf16 v[112:115], v[96:99], v[202:205], v[112:115]
	v_mfma_f32_16x16x32_bf16 v[104:107], v[154:157], v[202:205], v[104:107]
	v_mfma_f32_16x16x32_bf16 v[92:95], v[96:99], v[210:213], v[92:95]
	v_mfma_f32_16x16x32_bf16 v[84:87], v[154:157], v[210:213], v[84:87]
	v_mfma_f32_16x16x32_bf16 v[76:79], v[96:99], v[218:221], v[76:79]
	v_mfma_f32_16x16x32_bf16 v[68:71], v[154:157], v[218:221], v[68:71]
	v_mfma_f32_16x16x32_bf16 v[128:131], v[150:153], v[182:185], v[128:131]
	v_mfma_f32_16x16x32_bf16 v[120:123], v[158:161], v[182:185], v[120:123]
	v_mfma_f32_16x16x32_bf16 v[112:115], v[150:153], v[206:209], v[112:115]
	v_mfma_f32_16x16x32_bf16 v[104:107], v[158:161], v[206:209], v[104:107]
	v_mfma_f32_16x16x32_bf16 v[92:95], v[150:153], v[214:217], v[92:95]
	v_mfma_f32_16x16x32_bf16 v[84:87], v[158:161], v[214:217], v[84:87]
	v_mfma_f32_16x16x32_bf16 v[76:79], v[150:153], v[222:225], v[76:79]
	v_mfma_f32_16x16x32_bf16 v[68:71], v[158:161], v[222:225], v[68:71]
	s_setprio 0
	s_setprio 1
	v_mfma_f32_16x16x32_bf16 v[124:127], v[162:165], v[178:181], v[124:127]
	v_mfma_f32_16x16x32_bf16 v[116:119], v[170:173], v[178:181], v[116:119]
	v_mfma_f32_16x16x32_bf16 v[108:111], v[162:165], v[202:205], v[108:111]
	v_mfma_f32_16x16x32_bf16 v[100:103], v[170:173], v[202:205], v[100:103]
	v_mfma_f32_16x16x32_bf16 v[88:91], v[162:165], v[210:213], v[88:91]
	v_mfma_f32_16x16x32_bf16 v[80:83], v[170:173], v[210:213], v[80:83]
	v_mfma_f32_16x16x32_bf16 v[72:75], v[162:165], v[218:221], v[72:75]
	v_mfma_f32_16x16x32_bf16 v[64:67], v[170:173], v[218:221], v[64:67]
	v_mfma_f32_16x16x32_bf16 v[124:127], v[166:169], v[182:185], v[124:127]
	v_mfma_f32_16x16x32_bf16 v[116:119], v[174:177], v[182:185], v[116:119]
	v_mfma_f32_16x16x32_bf16 v[108:111], v[166:169], v[206:209], v[108:111]
	v_mfma_f32_16x16x32_bf16 v[100:103], v[174:177], v[206:209], v[100:103]
	v_mfma_f32_16x16x32_bf16 v[88:91], v[166:169], v[214:217], v[88:91]
	v_mfma_f32_16x16x32_bf16 v[80:83], v[174:177], v[214:217], v[80:83]
	v_mfma_f32_16x16x32_bf16 v[72:75], v[166:169], v[222:225], v[72:75]
	v_mfma_f32_16x16x32_bf16 v[64:67], v[174:177], v[222:225], v[64:67]
	s_setprio 0
	s_barrier
	s_add_i32 s30, s86, s56
	s_mov_b32 m0, s30
	ds_read_b128 v[178:181], v149 offset:16384
	ds_read_b128 v[182:185], v149 offset:17408
	ds_read_b128 v[202:205], v149 offset:18432
	ds_read_b128 v[206:209], v149 offset:19456
	ds_read_b128 v[210:213], v149 offset:20480
	ds_read_b128 v[214:217], v149 offset:21504
	ds_read_b128 v[218:221], v149 offset:22528
	ds_read_b128 v[222:225], v149 offset:23552
	global_load_lds_dwordx4 v188, s[36:37]
	s_add_i32 m0, s30, 0x2000
	s_add_u32 s30, s36, 0x40000
	s_addc_u32 s31, s37, 0
	s_add_i32 s76, s76, s56
	global_load_lds_dwordx4 v132, s[36:37]
	s_mov_b32 m0, s76
	s_nop 0
	global_load_lds_dwordx4 v188, s[30:31]
	s_add_i32 m0, s76, 0x2000
	s_nop 0
	global_load_lds_dwordx4 v132, s[30:31]
	s_mov_b32 m0, s60
	s_nop 0
	global_load_lds_dwordx4 v136, s[38:39]
	s_mov_b32 m0, s71
	s_nop 0
	global_load_lds_dwordx4 v134, s[38:39]
	s_waitcnt vmcnt(8)
	s_waitcnt lgkmcnt(0)
	s_barrier
	s_setprio 1
	s_waitcnt lgkmcnt(0)
	v_mfma_f32_16x16x32_bf16 v[60:63], v[96:99], v[178:181], v[60:63]
	v_mfma_f32_16x16x32_bf16 v[52:55], v[154:157], v[178:181], v[52:55]
	v_mfma_f32_16x16x32_bf16 v[44:47], v[96:99], v[202:205], v[44:47]
	v_mfma_f32_16x16x32_bf16 v[36:39], v[154:157], v[202:205], v[36:39]
	v_mfma_f32_16x16x32_bf16 v[28:31], v[96:99], v[210:213], v[28:31]
	v_mfma_f32_16x16x32_bf16 v[20:23], v[154:157], v[210:213], v[20:23]
	v_mfma_f32_16x16x32_bf16 v[12:15], v[96:99], v[218:221], v[12:15]
	v_mfma_f32_16x16x32_bf16 v[4:7], v[154:157], v[218:221], v[4:7]
	v_mfma_f32_16x16x32_bf16 v[60:63], v[150:153], v[182:185], v[60:63]
	v_mfma_f32_16x16x32_bf16 v[52:55], v[158:161], v[182:185], v[52:55]
	v_mfma_f32_16x16x32_bf16 v[44:47], v[150:153], v[206:209], v[44:47]
	v_mfma_f32_16x16x32_bf16 v[36:39], v[158:161], v[206:209], v[36:39]
	v_mfma_f32_16x16x32_bf16 v[28:31], v[150:153], v[214:217], v[28:31]
	v_mfma_f32_16x16x32_bf16 v[20:23], v[158:161], v[214:217], v[20:23]
	v_mfma_f32_16x16x32_bf16 v[12:15], v[150:153], v[222:225], v[12:15]
	v_mfma_f32_16x16x32_bf16 v[4:7], v[158:161], v[222:225], v[4:7]
	s_setprio 0
	s_setprio 1
	v_mfma_f32_16x16x32_bf16 v[56:59], v[162:165], v[178:181], v[56:59]
	v_mfma_f32_16x16x32_bf16 v[48:51], v[170:173], v[178:181], v[48:51]
	v_mfma_f32_16x16x32_bf16 v[40:43], v[162:165], v[202:205], v[40:43]
	v_mfma_f32_16x16x32_bf16 v[32:35], v[170:173], v[202:205], v[32:35]
	v_mfma_f32_16x16x32_bf16 v[24:27], v[162:165], v[210:213], v[24:27]
	v_mfma_f32_16x16x32_bf16 v[16:19], v[170:173], v[210:213], v[16:19]
	v_mfma_f32_16x16x32_bf16 v[8:11], v[162:165], v[218:221], v[8:11]
	v_mfma_f32_16x16x32_bf16 v[0:3], v[170:173], v[218:221], v[0:3]
	v_mfma_f32_16x16x32_bf16 v[56:59], v[166:169], v[182:185], v[56:59]
	v_mfma_f32_16x16x32_bf16 v[48:51], v[174:177], v[182:185], v[48:51]
	v_mfma_f32_16x16x32_bf16 v[40:43], v[166:169], v[206:209], v[40:43]
	v_mfma_f32_16x16x32_bf16 v[32:35], v[174:177], v[206:209], v[32:35]
	v_mfma_f32_16x16x32_bf16 v[24:27], v[166:169], v[214:217], v[24:27]
	v_mfma_f32_16x16x32_bf16 v[16:19], v[174:177], v[214:217], v[16:19]
	v_mfma_f32_16x16x32_bf16 v[8:11], v[166:169], v[222:225], v[8:11]
	v_mfma_f32_16x16x32_bf16 v[0:3], v[174:177], v[222:225], v[0:3]
	s_setprio 0
	s_barrier
	s_add_i32 s76, 0, 0x18000
	v_add_u32_e32 v138, s76, v141
	s_add_i32 s77, 0, 0x1c000
	ds_read_b128 v[96:99], v138
	ds_read_b128 v[150:153], v138 offset:1024
	ds_read_b128 v[154:157], v138 offset:2048
	ds_read_b128 v[158:161], v138 offset:3072
	v_add_u32_e32 v138, s77, v141
	ds_read_b128 v[162:165], v138
	ds_read_b128 v[166:169], v138 offset:1024
	ds_read_b128 v[170:173], v138 offset:2048
	ds_read_b128 v[174:177], v138 offset:3072
	s_add_u32 s30, s38, 0x40000
	s_addc_u32 s31, s39, 0
	s_mov_b32 m0, s87
	ds_read_b128 v[178:181], v149 offset:32768
	ds_read_b128 v[182:185], v149 offset:33792
	ds_read_b128 v[202:205], v149 offset:34816
	ds_read_b128 v[206:209], v149 offset:35840
	ds_read_b128 v[210:213], v149 offset:36864
	ds_read_b128 v[214:217], v149 offset:37888
	ds_read_b128 v[218:221], v149 offset:38912
	ds_read_b128 v[222:225], v149 offset:39936
	global_load_lds_dwordx4 v136, s[30:31]
	s_mov_b32 m0, s89
	s_nop 0
	global_load_lds_dwordx4 v134, s[30:31]
	s_waitcnt vmcnt(8)
	s_waitcnt lgkmcnt(0)
	s_barrier
	s_setprio 1
	s_waitcnt lgkmcnt(0)
	v_mfma_f32_16x16x32_bf16 v[128:131], v[96:99], v[178:181], v[128:131]
	v_mfma_f32_16x16x32_bf16 v[120:123], v[154:157], v[178:181], v[120:123]
	v_mfma_f32_16x16x32_bf16 v[112:115], v[96:99], v[202:205], v[112:115]
	v_mfma_f32_16x16x32_bf16 v[104:107], v[154:157], v[202:205], v[104:107]
	v_mfma_f32_16x16x32_bf16 v[92:95], v[96:99], v[210:213], v[92:95]
	v_mfma_f32_16x16x32_bf16 v[84:87], v[154:157], v[210:213], v[84:87]
	v_mfma_f32_16x16x32_bf16 v[76:79], v[96:99], v[218:221], v[76:79]
	v_mfma_f32_16x16x32_bf16 v[68:71], v[154:157], v[218:221], v[68:71]
	v_mfma_f32_16x16x32_bf16 v[128:131], v[150:153], v[182:185], v[128:131]
	v_mfma_f32_16x16x32_bf16 v[120:123], v[158:161], v[182:185], v[120:123]
	v_mfma_f32_16x16x32_bf16 v[112:115], v[150:153], v[206:209], v[112:115]
	v_mfma_f32_16x16x32_bf16 v[104:107], v[158:161], v[206:209], v[104:107]
	v_mfma_f32_16x16x32_bf16 v[92:95], v[150:153], v[214:217], v[92:95]
	v_mfma_f32_16x16x32_bf16 v[84:87], v[158:161], v[214:217], v[84:87]
	v_mfma_f32_16x16x32_bf16 v[76:79], v[150:153], v[222:225], v[76:79]
	v_mfma_f32_16x16x32_bf16 v[68:71], v[158:161], v[222:225], v[68:71]
	s_setprio 0
	s_setprio 1
	v_mfma_f32_16x16x32_bf16 v[124:127], v[162:165], v[178:181], v[124:127]
	v_mfma_f32_16x16x32_bf16 v[116:119], v[170:173], v[178:181], v[116:119]
	v_mfma_f32_16x16x32_bf16 v[108:111], v[162:165], v[202:205], v[108:111]
	v_mfma_f32_16x16x32_bf16 v[100:103], v[170:173], v[202:205], v[100:103]
	v_mfma_f32_16x16x32_bf16 v[88:91], v[162:165], v[210:213], v[88:91]
	v_mfma_f32_16x16x32_bf16 v[80:83], v[170:173], v[210:213], v[80:83]
	v_mfma_f32_16x16x32_bf16 v[72:75], v[162:165], v[218:221], v[72:75]
	v_mfma_f32_16x16x32_bf16 v[64:67], v[170:173], v[218:221], v[64:67]
	v_mfma_f32_16x16x32_bf16 v[124:127], v[166:169], v[182:185], v[124:127]
	v_mfma_f32_16x16x32_bf16 v[116:119], v[174:177], v[182:185], v[116:119]
	v_mfma_f32_16x16x32_bf16 v[108:111], v[166:169], v[206:209], v[108:111]
	v_mfma_f32_16x16x32_bf16 v[100:103], v[174:177], v[206:209], v[100:103]
	v_mfma_f32_16x16x32_bf16 v[88:91], v[166:169], v[214:217], v[88:91]
	v_mfma_f32_16x16x32_bf16 v[80:83], v[174:177], v[214:217], v[80:83]
	v_mfma_f32_16x16x32_bf16 v[72:75], v[166:169], v[222:225], v[72:75]
	v_mfma_f32_16x16x32_bf16 v[64:67], v[174:177], v[222:225], v[64:67]
	s_setprio 0
	s_barrier
	s_add_i32 s30, s76, s56
	s_add_u32 s100, s36, 0x80
	s_addc_u32 s101, s37, 0
	s_mov_b32 m0, s30
	ds_read_b128 v[178:181], v149 offset:49152
	ds_read_b128 v[182:185], v149 offset:50176
	ds_read_b128 v[202:205], v149 offset:51200
	ds_read_b128 v[206:209], v149 offset:52224
	ds_read_b128 v[210:213], v149 offset:53248
	ds_read_b128 v[214:217], v149 offset:54272
	ds_read_b128 v[218:221], v149 offset:55296
	ds_read_b128 v[222:225], v149 offset:56320
	global_load_lds_dwordx4 v188, s[100:101]
	s_add_i32 m0, s30, 0x2000
	s_add_u32 s30, s36, 0x40080
	s_addc_u32 s31, s37, 0
	s_add_i32 s36, s77, s56
	global_load_lds_dwordx4 v132, s[100:101]
	s_mov_b32 m0, s36
	s_nop 0
	global_load_lds_dwordx4 v188, s[30:31]
	s_add_i32 m0, s36, 0x2000
	s_nop 0
	global_load_lds_dwordx4 v132, s[30:31]
	s_add_u32 s100, s38, 0x80
	s_addc_u32 s101, s39, 0
	s_mov_b32 m0, s90
	s_nop 0
	global_load_lds_dwordx4 v136, s[100:101]
	s_mov_b32 m0, s91
	s_nop 0
	global_load_lds_dwordx4 v134, s[100:101]
	s_waitcnt vmcnt(8)
	s_waitcnt lgkmcnt(0)
	s_barrier
	s_setprio 1
	s_waitcnt lgkmcnt(0)
	v_mfma_f32_16x16x32_bf16 v[60:63], v[96:99], v[178:181], v[60:63]
	v_mfma_f32_16x16x32_bf16 v[52:55], v[154:157], v[178:181], v[52:55]
	v_mfma_f32_16x16x32_bf16 v[44:47], v[96:99], v[202:205], v[44:47]
	v_mfma_f32_16x16x32_bf16 v[36:39], v[154:157], v[202:205], v[36:39]
	v_mfma_f32_16x16x32_bf16 v[28:31], v[96:99], v[210:213], v[28:31]
	v_mfma_f32_16x16x32_bf16 v[20:23], v[154:157], v[210:213], v[20:23]
	v_mfma_f32_16x16x32_bf16 v[12:15], v[96:99], v[218:221], v[12:15]
	v_mfma_f32_16x16x32_bf16 v[4:7], v[154:157], v[218:221], v[4:7]
	v_mfma_f32_16x16x32_bf16 v[60:63], v[150:153], v[182:185], v[60:63]
	v_mfma_f32_16x16x32_bf16 v[52:55], v[158:161], v[182:185], v[52:55]
	v_mfma_f32_16x16x32_bf16 v[44:47], v[150:153], v[206:209], v[44:47]
	v_mfma_f32_16x16x32_bf16 v[36:39], v[158:161], v[206:209], v[36:39]
	v_mfma_f32_16x16x32_bf16 v[28:31], v[150:153], v[214:217], v[28:31]
	v_mfma_f32_16x16x32_bf16 v[20:23], v[158:161], v[214:217], v[20:23]
	v_mfma_f32_16x16x32_bf16 v[12:15], v[150:153], v[222:225], v[12:15]
	v_mfma_f32_16x16x32_bf16 v[4:7], v[158:161], v[222:225], v[4:7]
	s_setprio 0
	s_setprio 1
	v_mfma_f32_16x16x32_bf16 v[56:59], v[162:165], v[178:181], v[56:59]
	v_mfma_f32_16x16x32_bf16 v[48:51], v[170:173], v[178:181], v[48:51]
	v_mfma_f32_16x16x32_bf16 v[40:43], v[162:165], v[202:205], v[40:43]
	v_mfma_f32_16x16x32_bf16 v[32:35], v[170:173], v[202:205], v[32:35]
	v_mfma_f32_16x16x32_bf16 v[24:27], v[162:165], v[210:213], v[24:27]
	v_mfma_f32_16x16x32_bf16 v[16:19], v[170:173], v[210:213], v[16:19]
	v_mfma_f32_16x16x32_bf16 v[8:11], v[162:165], v[218:221], v[8:11]
	v_mfma_f32_16x16x32_bf16 v[0:3], v[170:173], v[218:221], v[0:3]
	v_mfma_f32_16x16x32_bf16 v[56:59], v[166:169], v[182:185], v[56:59]
	v_mfma_f32_16x16x32_bf16 v[48:51], v[174:177], v[182:185], v[48:51]
	v_mfma_f32_16x16x32_bf16 v[40:43], v[166:169], v[206:209], v[40:43]
	v_mfma_f32_16x16x32_bf16 v[32:35], v[174:177], v[206:209], v[32:35]
	v_mfma_f32_16x16x32_bf16 v[24:27], v[166:169], v[214:217], v[24:27]
	v_mfma_f32_16x16x32_bf16 v[16:19], v[174:177], v[214:217], v[16:19]
	v_mfma_f32_16x16x32_bf16 v[8:11], v[166:169], v[222:225], v[8:11]
	v_mfma_f32_16x16x32_bf16 v[0:3], v[174:177], v[222:225], v[0:3]
	s_setprio 0
	s_barrier
	s_add_i32 s43, s43, 2
	s_cmp_gt_u32 s43, 13
	s_mov_b64 s[30:31], s[34:35]
	s_cbranch_scc0 .LBB0_528

	.amdhsa_kernel _Z6mk_fwd6Params
		.amdhsa_group_segment_fixed_size 0
		.amdhsa_private_segment_fixed_size 0
		.amdhsa_kernarg_size 488
		.amdhsa_user_sgpr_count 2
		.amdhsa_user_sgpr_dispatch_ptr 0
		.amdhsa_user_sgpr_queue_ptr 0
		.amdhsa_user_sgpr_kernarg_segment_ptr 1
		.amdhsa_user_sgpr_dispatch_id 0
		.amdhsa_user_sgpr_kernarg_preload_length 0
		.amdhsa_user_sgpr_kernarg_preload_offset 0
		.amdhsa_user_sgpr_private_segment_size 0
		.amdhsa_uses_dynamic_stack 0
		.amdhsa_enable_private_segment 0
		.amdhsa_system_sgpr_workgroup_id_x 1
		.amdhsa_system_sgpr_workgroup_id_y 0
		.amdhsa_system_sgpr_workgroup_id_z 0
		.amdhsa_system_sgpr_workgroup_info 0
		.amdhsa_system_vgpr_workitem_id 2
		.amdhsa_next_free_vgpr 256
		.amdhsa_next_free_sgpr 102
		.amdhsa_accum_offset 256
		.amdhsa_reserve_vcc 1
		.amdhsa_float_round_mode_32 0
		.amdhsa_float_round_mode_16_64 0
		.amdhsa_float_denorm_mode_32 3
		.amdhsa_float_denorm_mode_16_64 3
		.amdhsa_dx10_clamp 1
		.amdhsa_ieee_mode 1
		.amdhsa_fp16_overflow 0
		.amdhsa_tg_split 0
		.amdhsa_exception_fp_ieee_invalid_op 0
		.amdhsa_exception_fp_denorm_src 0
		.amdhsa_exception_fp_ieee_div_zero 0
		.amdhsa_exception_fp_ieee_overflow 0
		.amdhsa_exception_fp_ieee_underflow 0
		.amdhsa_exception_fp_ieee_inexact 0
		.amdhsa_exception_int_div_zero 0
	.end_amdhsa_kernel

.Lfunc_end0:
	.size	_Z6mk_fwd6Params, .Lfunc_end0-_Z6mk_fwd6Params
	.set _Z6mk_fwd6Params.num_vgpr, 256
	.set _Z6mk_fwd6Params.num_agpr, 0
	.set _Z6mk_fwd6Params.numbered_sgpr, 102
	.set _Z6mk_fwd6Params.num_named_barrier, 0
	.set _Z6mk_fwd6Params.private_seg_size, 0
	.set _Z6mk_fwd6Params.uses_vcc, 1
	.set _Z6mk_fwd6Params.uses_flat_scratch, 0
	.set _Z6mk_fwd6Params.has_dyn_sized_stack, 0
	.set _Z6mk_fwd6Params.has_recursion, 0
	.set _Z6mk_fwd6Params.has_indirect_call, 0

amdhsa.kernels:
  - .agpr_count:     0
    .args:
      - .offset:         0
        .size:           232
        .value_kind:     by_value
      - .offset:         232
        .size:           4
        .value_kind:     hidden_block_count_x
      - .offset:         236
        .size:           4
        .value_kind:     hidden_block_count_y
      - .offset:         240
        .size:           4
        .value_kind:     hidden_block_count_z
      - .offset:         244
        .size:           2
        .value_kind:     hidden_group_size_x
      - .offset:         246
        .size:           2
        .value_kind:     hidden_group_size_y
      - .offset:         248
        .size:           2
        .value_kind:     hidden_group_size_z
      - .offset:         250
        .size:           2
        .value_kind:     hidden_remainder_x
      - .offset:         252
        .size:           2
        .value_kind:     hidden_remainder_y
      - .offset:         254
        .size:           2
        .value_kind:     hidden_remainder_z
      - .offset:         272
        .size:           8
        .value_kind:     hidden_global_offset_x
      - .offset:         280
        .size:           8
        .value_kind:     hidden_global_offset_y
      - .offset:         288
        .size:           8
        .value_kind:     hidden_global_offset_z
      - .offset:         296
        .size:           2
        .value_kind:     hidden_grid_dims
      - .offset:         320
        .size:           8
        .value_kind:     hidden_multigrid_sync_arg
      - .offset:         352
        .size:           4
        .value_kind:     hidden_dynamic_lds_size
    .group_segment_fixed_size: 0
    .kernarg_segment_align: 8
    .kernarg_segment_size: 488
    .language:       OpenCL C
    .language_version:
      - 2
      - 0
    .max_flat_workgroup_size: 512
    .name:           _Z6mk_fwd6Params
    .private_segment_fixed_size: 0
    .sgpr_count:     108
    .sgpr_spill_count: 60
    .symbol:         _Z6mk_fwd6Params.kd
    .uniform_work_group_size: 1
    .uses_dynamic_stack: false
    .vgpr_count:     256
    .vgpr_spill_count: 0
    .wavefront_size: 64
